# diff-attention loop: end-of-step LDS wait and row-max finalize deferred to after the step barrier (overlaps bpermute/LDS latency with the barrier wait)
# speedup vs baseline: 1.0126x; 1.0082x over previous
; #define LAS __attribute__((address_space(3)))
; __device__ __forceinline__ bf16x8 vfrag(LAS const unsigned char* vl, int off) { const s16x4 lo = vtr(vl + off), hi = vtr(vl + off + 512); return (bf16x8){lo[0], lo[1], lo[2], lo[3], hi[0], hi[1], hi[2], hi[3]}; }
; #define STEP_SYNC(j) do { \
;         if ((j) + 2 < NT) asm volatile("s_waitcnt vmcnt(4)\n\ts_barrier" ::: "memory"); else asm volatile("s_waitcnt vmcnt(0)\n\ts_barrier" ::: "memory"); \
;         if ((j) + 3 < NT) STAGE_K((j) + 3); if ((j) + 2 < NT) STAGE_V((j) + 2); } while (0)
; __device__ __forceinline__ void diff_unit(int b, int h, int qb, bool asc, const bf16_t* DQ, const bf16_t* DK, const bf16_t* DV, bf16_t* ATT, float lam, const float* subg,
;                                           LAS unsigned char* lds, int wid, int lane) {
;     ...
;     for (int j = j0; j <= j1; ++j) {
;         STEP_SYNC(j);
;         TOP_CHECK(sc);
;         if (j == j0) {
;             LAS const unsigned char* v0_ = lds + VOFF + (j & 3) * KSL + vlane;
; #pragma unroll
;             for (int d0 = 0; d0 < 4; ++d0) { vfa[d0][0] = vfrag(v0_, d0 * 4096); vfa[d0][1] = vfrag(v0_, d0 * 4096 + 1024); }
;         }
;         BLOCK(sc, sn, vfa, vfb, j & 3, 1, j & 3, 0);
;         TOP_CHECK(sn);
;         BLOCK(sn, sc, vfb, vfa, (j + 1) & 3, 0, j & 3, 1);
.LBB0_500:
	v_cvt_pk_bf16_f32 v66, v128, v129
	v_mov_b32_e32 v81, v64
	v_mov_b32_e32 v82, v64
	v_mov_b32_e32 v83, v64
	v_mov_b32_e32 v84, v64
	v_mov_b32_e32 v85, v64
	v_mov_b32_e32 v86, v64
	v_mov_b32_e32 v87, v64
	v_mov_b32_e32 v88, v64
	v_mov_b32_e32 v89, v64
	v_mov_b32_e32 v90, v64
	v_mov_b32_e32 v91, v64
	v_mov_b32_e32 v92, v64
	v_mov_b32_e32 v93, v64
	v_mov_b32_e32 v94, v64
	v_mov_b32_e32 v95, v64
	v_cvt_pk_bf16_f32 v67, v130, v131
	v_cvt_pk_bf16_f32 v68, v160, v161
	v_cvt_pk_bf16_f32 v69, v168, v169
	v_cvt_pk_bf16_f32 v70, v166, v167
	v_cvt_pk_bf16_f32 v71, v170, v171
	v_cvt_pk_bf16_f32 v72, v172, v173
	v_cvt_pk_bf16_f32 v73, v174, v175
	s_addk_i32 s3, 0x4000
	v_mfma_f32_32x32x16_bf16 v[0:15], v[66:69], v[132:135], v[0:15]
	ds_read_b64_tr_b16 v[128:129], v176 offset:2048
	ds_read_b64_tr_b16 v[130:131], v176 offset:2560
	v_add_u32_e32 v74, s3, v228
	v_add_u32_e32 v180, s3, v229
	v_add_u32_e32 v181, s3, v230
	v_exp_f32_e32 v78, v96
	v_exp_f32_e32 v79, v97
	v_mfma_f32_32x32x16_bf16 v[0:15], v[70:73], v[136:139], v[0:15]
	ds_read_b64_tr_b16 v[132:133], v176 offset:3072
	ds_read_b64_tr_b16 v[134:135], v176 offset:3584
	v_exp_f32_e32 v166, v98
	v_exp_f32_e32 v167, v99
	v_mfma_f32_32x32x16_bf16 v[32:47], v[66:69], v[140:143], v[32:47]
	ds_read_b64_tr_b16 v[136:137], v176 offset:6144
	ds_read_b64_tr_b16 v[138:139], v176 offset:6656
	v_exp_f32_e32 v168, v100
	v_exp_f32_e32 v169, v101
	v_mfma_f32_32x32x16_bf16 v[32:47], v[70:73], v[144:147], v[32:47]
	ds_read_b64_tr_b16 v[140:141], v176 offset:7168
	ds_read_b64_tr_b16 v[142:143], v176 offset:7680
	v_exp_f32_e32 v170, v102
	v_exp_f32_e32 v171, v103
	v_mfma_f32_32x32x16_bf16 v[48:63], v[66:69], v[148:151], v[48:63]
	ds_read_b64_tr_b16 v[144:145], v176 offset:10240
	ds_read_b64_tr_b16 v[146:147], v176 offset:10752
	v_exp_f32_e32 v172, v104
	v_exp_f32_e32 v173, v105
	v_mfma_f32_32x32x16_bf16 v[48:63], v[70:73], v[152:155], v[48:63]
	ds_read_b64_tr_b16 v[148:149], v176 offset:11264
	ds_read_b64_tr_b16 v[150:151], v176 offset:11776
	ds_read_b128 v[74:77], v74
	v_exp_f32_e32 v174, v106
	v_exp_f32_e32 v175, v107
	v_mfma_f32_32x32x16_bf16 v[16:31], v[66:69], v[156:159], v[16:31]
	ds_read_b64_tr_b16 v[152:153], v176 offset:14336
	ds_read_b64_tr_b16 v[154:155], v176 offset:14848
	v_exp_f32_e32 v178, v108
	v_exp_f32_e32 v179, v109
	v_pk_add_f32 v[66:67], v[78:79], 0 op_sel_hi:[1,0]
	v_mfma_f32_32x32x16_bf16 v[16:31], v[70:73], v[162:165], v[16:31]
	v_add_f32_e64 v66, v166, v66
	v_add_f32_e64 v67, v167, v67
	ds_read_b64_tr_b16 v[156:157], v176 offset:15360
	ds_read_b64_tr_b16 v[158:159], v176 offset:15872
	v_add_f32_e64 v66, v168, v66
	v_add_f32_e64 v67, v169, v67
	v_exp_f32_e32 v176, v110
	v_pk_add_f32 v[66:67], v[170:171], v[66:67]
	v_exp_f32_e32 v177, v111
	v_pk_add_f32 v[66:67], v[172:173], v[66:67]
	v_cvt_pk_bf16_f32 v160, v78, v79
	v_pk_add_f32 v[78:79], v[174:175], v[66:67]
	ds_read_b128 v[66:69], v180
	ds_read_b128 v[70:73], v181
	v_cvt_pk_bf16_f32 v161, v166, v167
	v_cvt_pk_bf16_f32 v162, v168, v169
	v_cvt_pk_bf16_f32 v163, v170, v171
	v_cvt_pk_bf16_f32 v164, v172, v173
	v_cvt_pk_bf16_f32 v165, v174, v175
	v_pk_add_f32 v[78:79], v[178:179], v[78:79]
	v_cvt_pk_bf16_f32 v166, v178, v179
	v_cvt_pk_bf16_f32 v167, v176, v177
	v_pk_add_f32 v[78:79], v[176:177], v[78:79]
	s_waitcnt lgkmcnt(6)
	v_mfma_f32_32x32x16_bf16 v[80:95], v[74:77], v[112:115], v[80:95]
	v_add_f32_e32 v78, v78, v79
	v_add_f32_e32 v235, v65, v78
	v_add_u32_e32 v65, s3, v231
	v_max3_f32 v168, v96, v97, v98
	v_max3_f32 v100, v99, v100, v101
	ds_read_b128 v[96:99], v65
	s_waitcnt lgkmcnt(2)
	v_mfma_f32_32x32x16_bf16 v[80:95], v[66:69], v[116:119], v[80:95]
	v_max3_f32 v65, v168, v102, v103
	v_max3_f32 v74, v100, v104, v105
	s_waitcnt lgkmcnt(1)
	v_mfma_f32_32x32x16_bf16 v[80:95], v[70:73], v[120:123], v[80:95]
	v_max3_f32 v65, v65, v106, v107
	v_max3_f32 v66, v74, v108, v109
	s_nop 0
	v_max3_f32 v65, v65, v110, v111
	s_waitcnt lgkmcnt(0)
	v_mfma_f32_32x32x16_bf16 v[80:95], v[96:99], v[124:127], v[80:95]
	v_max_f32_e32 v66, v66, v66
	v_max_f32_e32 v65, v65, v65
	v_max_f32_e32 v65, v65, v66
	ds_bpermute_b32 v66, v214, v65
	s_cmp_ge_u32 s76, s84
	s_cbranch_scc1 .LBB0_527
	s_waitcnt lgkmcnt(0)
	v_max_f32_e32 v66, v66, v66
	v_max_f32_e32 v65, v65, v65
	s_sub_i32 s3, s18, s76
	v_cmp_gt_u32_e64 s[4:5], 32, v207
	v_lshl_add_u32 v236, v225, 2, s53
	v_lshl_add_u32 v237, v206, 2, s53
	v_max_f32_e32 v96, v65, v66
	s_bitset1_b32 s2, 15
	s_add_i32 s3, s3, -3
	v_mov_b32_e32 v65, v64
	v_mov_b32_e32 v66, v64
	v_mov_b32_e32 v67, v64
	v_mov_b32_e32 v68, v64
	v_mov_b32_e32 v69, v64
	v_mov_b32_e32 v70, v64
	v_mov_b32_e32 v71, v64
	v_mov_b32_e32 v72, v64
	v_mov_b32_e32 v73, v64
	v_mov_b32_e32 v74, v64
	v_mov_b32_e32 v75, v64
	v_mov_b32_e32 v76, v64
	v_mov_b32_e32 v77, v64
	v_mov_b32_e32 v78, v64
	v_mov_b32_e32 v79, v64
	v_mov_b32_e32 v100, v96
	v_mov_b32_e32 v101, v96

.Lhd_bar:
	s_barrier
	s_waitcnt lgkmcnt(0)
	v_max_f32_e32 v96, v100, v101

.LBB0_512:
	s_and_b32 s20, s2, 0xc000
	s_add_i32 s20, s65, s20
	v_mfma_f32_32x32x16_bf16 v[0:15], v[156:159], v[196:199], v[0:15]
	ds_read_b64_tr_b16 v[128:129], v238 offset:2048
	ds_read_b64_tr_b16 v[130:131], v238 offset:2560
	v_exp_f32_e32 v160, v96
	v_exp_f32_e32 v161, v97
	v_add_u32_e32 v152, s20, v228
	v_add_u32_e32 v239, s20, v229
	v_add_u32_e32 v240, s20, v230
	v_mfma_f32_32x32x16_bf16 v[0:15], v[162:165], v[192:195], v[0:15]
	ds_read_b64_tr_b16 v[132:133], v238 offset:3072
	ds_read_b64_tr_b16 v[134:135], v238 offset:3584
	v_exp_f32_e32 v166, v98
	v_exp_f32_e32 v167, v99
	v_mfma_f32_32x32x16_bf16 v[32:47], v[156:159], v[188:191], v[32:47]
	ds_read_b64_tr_b16 v[136:137], v238 offset:6144
	ds_read_b64_tr_b16 v[138:139], v238 offset:6656
	v_exp_f32_e32 v192, v100
	v_exp_f32_e32 v193, v101
	v_mfma_f32_32x32x16_bf16 v[32:47], v[162:165], v[184:187], v[32:47]
	ds_read_b64_tr_b16 v[140:141], v238 offset:7168
	ds_read_b64_tr_b16 v[142:143], v238 offset:7680
	v_exp_f32_e32 v188, v102
	v_exp_f32_e32 v189, v103
	v_mfma_f32_32x32x16_bf16 v[48:63], v[156:159], v[180:183], v[48:63]
	ds_read_b64_tr_b16 v[144:145], v238 offset:10240
	ds_read_b64_tr_b16 v[146:147], v238 offset:10752
	v_exp_f32_e32 v184, v104
	v_exp_f32_e32 v185, v105
	v_mfma_f32_32x32x16_bf16 v[48:63], v[162:165], v[176:179], v[48:63]
	ds_read_b64_tr_b16 v[148:149], v238 offset:11264
	ds_read_b64_tr_b16 v[150:151], v238 offset:11776
	ds_read_b128 v[180:183], v152
	v_exp_f32_e32 v186, v106
	v_exp_f32_e32 v187, v107
	v_mfma_f32_32x32x16_bf16 v[16:31], v[156:159], v[172:175], v[16:31]
	ds_read_b64_tr_b16 v[152:153], v238 offset:14336
	ds_read_b64_tr_b16 v[154:155], v238 offset:14848
	v_exp_f32_e32 v176, v108
	v_exp_f32_e32 v177, v109
	v_mfma_f32_32x32x16_bf16 v[16:31], v[162:165], v[168:171], v[16:31]
	ds_read_b64_tr_b16 v[156:157], v238 offset:15360
	ds_read_b64_tr_b16 v[158:159], v238 offset:15872
	v_add_f32_e32 v162, v166, v160
	v_add_f32_e32 v163, v167, v161
	v_exp_f32_e32 v178, v110
	v_exp_f32_e32 v179, v111
	v_pk_add_f32 v[164:165], v[192:193], v[162:163]
	ds_read_b128 v[168:171], v239
	ds_read_b128 v[172:175], v240
	v_pk_add_f32 v[164:165], v[188:189], v[164:165]
	v_cvt_pk_bf16_f32 v160, v160, v161
	v_cvt_pk_bf16_f32 v161, v166, v167
	v_pk_add_f32 v[166:167], v[184:185], v[164:165]
	v_cvt_pk_bf16_f32 v162, v192, v193
	v_pk_add_f32 v[166:167], v[186:187], v[166:167]
	v_cvt_pk_bf16_f32 v163, v188, v189
	v_cvt_pk_bf16_f32 v164, v184, v185
	v_cvt_pk_bf16_f32 v165, v186, v187
	v_pk_add_f32 v[184:185], v[176:177], v[166:167]
	v_cvt_pk_bf16_f32 v166, v176, v177
	v_cvt_pk_bf16_f32 v167, v178, v179
	v_pk_add_f32 v[176:177], v[178:179], v[184:185]
	s_waitcnt lgkmcnt(6)
	v_mfma_f32_32x32x16_bf16 v[80:95], v[180:183], v[112:115], v[64:79]
	v_max3_f32 v178, v96, v97, v98
	v_add_f32_e32 v96, v176, v177
	v_add_f32_e32 v235, v235, v96
	v_add_u32_e32 v96, s20, v231
	v_max3_f32 v100, v99, v100, v101
	ds_read_b128 v[96:99], v96
	s_waitcnt lgkmcnt(2)
	v_mfma_f32_32x32x16_bf16 v[80:95], v[168:171], v[116:119], v[80:95]
	v_max3_f32 v101, v178, v102, v103
	v_max3_f32 v100, v100, v104, v105
	s_waitcnt lgkmcnt(1)
	v_mfma_f32_32x32x16_bf16 v[80:95], v[172:175], v[120:123], v[80:95]
	v_max3_f32 v101, v101, v106, v107
	v_max3_f32 v100, v100, v108, v109
	s_nop 0
	v_max3_f32 v101, v101, v110, v111
	v_max_f32_e32 v100, v101, v100
	s_waitcnt lgkmcnt(0)
	v_mfma_f32_32x32x16_bf16 v[80:95], v[96:99], v[124:127], v[80:95]
	ds_bpermute_b32 v101, v214, v100
	s_addk_i32 s2, 0x4000
	s_add_i32 s3, s3, -1
	s_cmp_ge_u32 s37, s84
	s_cbranch_scc1 .LBB0_527
	s_mov_b32 s76, s37
	s_branch .LBB0_502

; #define MFMA32(a, b, c) __builtin_amdgcn_mfma_f32_32x32x16_bf16((a), (b), (c), 0, 0, 0)
; __device__ __forceinline__ void diff_unit(int b, int h, int qb, bool asc, const bf16_t* DQ, const bf16_t* DK, const bf16_t* DV, bf16_t* ATT, float lam, const float* subg,
;                                           LAS unsigned char* lds, int wid, int lane) {
;     ...
;     {
;         if (pend) { rm = 0.f; TOP_CHECK(sc); }
; #pragma unroll
;         for (int d0 = 0; d0 < 4; ++d0) { O[d0] = MFMA32(__builtin_bit_cast(bf16x8, pwa), vfa[d0][0], O[d0]); O[d0] = MFMA32(__builtin_bit_cast(bf16x8, pwb), vfa[d0][1], O[d0]); }
.LBB0_527:
	s_waitcnt lgkmcnt(0)
	s_and_b64 vcc, exec, s[0:1]
	v_cmp_gt_u32_e64 s[0:1], 32, v207
	s_cbranch_vccz .LBB0_531
	s_and_saveexec_b64 s[4:5], s[0:1]
	v_lshl_add_u32 v64, v225, 2, s53
	ds_write_b32 v64, v232
	s_or_b64 exec, exec, s[4:5]
	s_waitcnt lgkmcnt(0)
	v_lshl_add_u32 v76, v206, 2, s53
	s_waitcnt lgkmcnt(0)
	ds_read_b128 v[64:67], v76 offset:96
	ds_read_b128 v[68:71], v76 offset:64
	ds_read_b128 v[72:75], v76 offset:32
	ds_read_b128 v[76:79], v76
	s_waitcnt lgkmcnt(0)
	s_waitcnt lgkmcnt(3)
	v_pk_mul_f32 v[14:15], v[14:15], v[66:67]
	s_waitcnt lgkmcnt(2)
	v_pk_mul_f32 v[10:11], v[10:11], v[70:71]
	s_waitcnt lgkmcnt(1)
	v_pk_mul_f32 v[6:7], v[6:7], v[74:75]
	s_waitcnt lgkmcnt(0)
	v_pk_mul_f32 v[2:3], v[2:3], v[78:79]
	v_pk_mul_f32 v[12:13], v[12:13], v[64:65]
	v_pk_mul_f32 v[8:9], v[8:9], v[68:69]
	v_pk_mul_f32 v[4:5], v[4:5], v[72:73]
	v_pk_mul_f32 v[0:1], v[0:1], v[76:77]
	v_pk_mul_f32 v[46:47], v[46:47], v[66:67]
	v_pk_mul_f32 v[42:43], v[42:43], v[70:71]
	v_pk_mul_f32 v[38:39], v[38:39], v[74:75]
	v_pk_mul_f32 v[34:35], v[34:35], v[78:79]
	v_pk_mul_f32 v[44:45], v[44:45], v[64:65]
	v_pk_mul_f32 v[40:41], v[40:41], v[68:69]
	v_pk_mul_f32 v[36:37], v[36:37], v[72:73]
	v_pk_mul_f32 v[32:33], v[32:33], v[76:77]
	v_pk_mul_f32 v[62:63], v[62:63], v[66:67]
	v_pk_mul_f32 v[58:59], v[58:59], v[70:71]
	v_pk_mul_f32 v[54:55], v[54:55], v[74:75]
	v_pk_mul_f32 v[50:51], v[50:51], v[78:79]
	v_pk_mul_f32 v[60:61], v[60:61], v[64:65]
	v_pk_mul_f32 v[56:57], v[56:57], v[68:69]
	v_pk_mul_f32 v[52:53], v[52:53], v[72:73]
	v_pk_mul_f32 v[48:49], v[48:49], v[76:77]
	v_pk_mul_f32 v[30:31], v[30:31], v[66:67]
	v_pk_mul_f32 v[26:27], v[26:27], v[70:71]
	v_pk_mul_f32 v[22:23], v[22:23], v[74:75]
	v_pk_mul_f32 v[18:19], v[18:19], v[78:79]
	v_pk_mul_f32 v[28:29], v[28:29], v[64:65]
	v_pk_mul_f32 v[24:25], v[24:25], v[68:69]
	v_pk_mul_f32 v[20:21], v[20:21], v[72:73]
	v_pk_mul_f32 v[16:17], v[16:17], v[76:77]
